# v51-lds-dma-skipdup
# speedup vs baseline: 1.0074x; 1.0007x over previous
.Ldf_qk:
	s_waitcnt lgkmcnt(7)
	v_mfma_f32_32x32x16_bf16 v[82:97], v[194:197], v[158:161], v[2:17]
	s_waitcnt lgkmcnt(6)
	ds_read_b128 v[194:197], v230 offset:17408
	s_add_u32 s98, s44, s58
	s_addc_u32 s99, s45, 0
	s_add_u32 s98, s98, s74
	s_addc_u32 s99, s99, s75
	s_add_u32 s98, s98, s26
	s_addc_u32 s99, s99, s27
	s_lshl_b32 s100, s90, 10
	s_add_i32 s100, s100, s12
	s_add_i32 m0, s100, 0x0
	s_nop 0
	global_load_lds_dwordx4 v238, s[98:99]
	v_mfma_f32_32x32x16_bf16 v[82:97], v[198:201], v[154:157], v[82:97]
	s_waitcnt lgkmcnt(6)
	ds_read_b128 v[198:201], v230 offset:17440
	v_mfma_f32_32x32x16_bf16 v[82:97], v[202:205], v[150:153], v[82:97]
	s_waitcnt lgkmcnt(6)
	ds_read_b128 v[202:205], v230 offset:17472
	s_add_i32 m0, s100, 0x2000
	s_nop 0
	global_load_lds_dwordx4 v239, s[98:99]
	v_mfma_f32_32x32x16_bf16 v[82:97], v[206:209], v[146:149], v[82:97]
	s_waitcnt lgkmcnt(6)
	ds_read_b128 v[206:209], v230 offset:17504
	v_mfma_f32_32x32x16_bf16 v[98:113], v[210:213], v[158:161], v[2:17]
	s_waitcnt lgkmcnt(6)
	ds_read_b128 v[210:213], v230 offset:26112
	s_add_i32 m0, s100, 0x4000
	s_nop 0
	global_load_lds_dwordx4 v240, s[98:99]
	v_mfma_f32_32x32x16_bf16 v[98:113], v[214:217], v[154:157], v[98:113]
	s_waitcnt lgkmcnt(6)
	ds_read_b128 v[214:217], v230 offset:26144
	v_mfma_f32_32x32x16_bf16 v[98:113], v[218:221], v[150:153], v[98:113]
	s_waitcnt lgkmcnt(6)
	ds_read_b128 v[218:221], v230 offset:26176
	s_add_i32 m0, s100, 0x6000
	s_nop 0
	global_load_lds_dwordx4 v241, s[98:99]
	v_mfma_f32_32x32x16_bf16 v[98:113], v[226:229], v[146:149], v[98:113]
	s_waitcnt lgkmcnt(6)
	ds_read_b128 v[226:229], v230 offset:26208
	v_mfma_f32_32x32x16_bf16 v[114:129], v[194:197], v[158:161], v[2:17]
	s_waitcnt lgkmcnt(6)
	ds_read_b64_tr_b16 v[194:195], v231 offset:34816
	ds_read_b64_tr_b16 v[196:197], v231 offset:37376
	v_exp_f32_e32 v82, v82
	v_exp_f32_e32 v83, v83
	s_add_i32 m0, s100, 0x8000
	s_nop 0
	global_load_lds_dwordx4 v242, s[98:99]
	v_add_f32_e32 v191, v191, v82
	v_add_f32_e32 v235, v235, v83
	v_cvt_pk_bf16_f32 v82, v82, v83
	v_mfma_f32_32x32x16_bf16 v[114:129], v[198:201], v[154:157], v[114:129]
	s_waitcnt lgkmcnt(7)
	ds_read_b64_tr_b16 v[198:199], v231 offset:34880
	ds_read_b64_tr_b16 v[200:201], v231 offset:37440
	v_exp_f32_e32 v84, v84
	v_exp_f32_e32 v85, v85
	v_add_f32_e32 v191, v191, v84
	v_add_f32_e32 v235, v235, v85
	v_cvt_pk_bf16_f32 v83, v84, v85
	v_mfma_f32_32x32x16_bf16 v[114:129], v[202:205], v[150:153], v[114:129]
	s_waitcnt lgkmcnt(8)
	ds_read_b64_tr_b16 v[202:203], v231 offset:34944
	ds_read_b64_tr_b16 v[204:205], v231 offset:37504
	v_exp_f32_e32 v86, v86
	v_exp_f32_e32 v87, v87
	s_add_i32 m0, s100, 0xa000
	s_nop 0
	global_load_lds_dwordx4 v243, s[98:99]
	v_add_f32_e32 v191, v191, v86
	v_add_f32_e32 v235, v235, v87
	v_cvt_pk_bf16_f32 v84, v86, v87
	v_mfma_f32_32x32x16_bf16 v[114:129], v[206:209], v[146:149], v[114:129]
	s_waitcnt lgkmcnt(9)
	ds_read_b64_tr_b16 v[206:207], v231 offset:35008
	ds_read_b64_tr_b16 v[208:209], v231 offset:37568
	v_exp_f32_e32 v88, v88
	v_exp_f32_e32 v89, v89
	v_add_f32_e32 v191, v191, v88
	v_add_f32_e32 v235, v235, v89
	v_cvt_pk_bf16_f32 v85, v88, v89
	v_mfma_f32_32x32x16_bf16 v[130:145], v[210:213], v[158:161], v[2:17]
	s_waitcnt lgkmcnt(10)
	ds_read_b64_tr_b16 v[210:211], v231 offset:39936
	ds_read_b64_tr_b16 v[212:213], v231 offset:42496
	v_exp_f32_e32 v90, v90
	v_exp_f32_e32 v91, v91
	s_add_i32 m0, s100, 0xc000
	s_nop 0
	global_load_lds_dwordx4 v244, s[98:99]
	v_add_f32_e32 v191, v191, v90
	v_add_f32_e32 v235, v235, v91
	v_cvt_pk_bf16_f32 v86, v90, v91
	v_mfma_f32_32x32x16_bf16 v[130:145], v[214:217], v[154:157], v[130:145]
	s_waitcnt lgkmcnt(11)
	ds_read_b64_tr_b16 v[214:215], v231 offset:40000
	ds_read_b64_tr_b16 v[216:217], v231 offset:42560
	v_exp_f32_e32 v92, v92
	v_exp_f32_e32 v93, v93
	v_add_f32_e32 v191, v191, v92
	v_add_f32_e32 v235, v235, v93
	v_cvt_pk_bf16_f32 v87, v92, v93
	v_mfma_f32_32x32x16_bf16 v[130:145], v[218:221], v[150:153], v[130:145]
	s_waitcnt lgkmcnt(12)
	ds_read_b64_tr_b16 v[218:219], v231 offset:40064
	ds_read_b64_tr_b16 v[220:221], v231 offset:42624
	v_exp_f32_e32 v94, v94
	v_exp_f32_e32 v95, v95
	s_add_i32 m0, s100, 0xe000
	s_nop 0
	global_load_lds_dwordx4 v245, s[98:99]
	v_add_f32_e32 v191, v191, v94
	v_add_f32_e32 v235, v235, v95
	v_cvt_pk_bf16_f32 v88, v94, v95
	v_mfma_f32_32x32x16_bf16 v[130:145], v[226:229], v[146:149], v[130:145]
	s_waitcnt lgkmcnt(12)
	ds_read_b64_tr_b16 v[226:227], v231 offset:40128
	ds_read_b64_tr_b16 v[228:229], v231 offset:42688
	v_exp_f32_e32 v96, v96
	v_exp_f32_e32 v97, v97
	v_add_f32_e32 v191, v191, v96
	v_add_f32_e32 v235, v235, v97
	v_cvt_pk_bf16_f32 v89, v96, v97
	v_mfma_f32_32x32x16_bf16 v[50:65], v[194:197], v[82:85], v[50:65]
	s_waitcnt lgkmcnt(12)
	ds_read_b64_tr_b16 v[194:195], v231 offset:45056
	ds_read_b64_tr_b16 v[196:197], v231 offset:47616
	v_exp_f32_e32 v98, v98
	v_exp_f32_e32 v99, v99
	s_add_i32 m0, s100, 0x10000
	s_nop 0
	global_load_lds_dwordx4 v246, s[98:99]
	v_add_f32_e32 v191, v191, v98
	v_add_f32_e32 v235, v235, v99
	v_cvt_pk_bf16_f32 v98, v98, v99
	v_mfma_f32_32x32x16_bf16 v[66:81], v[198:201], v[82:85], v[66:81]
	s_waitcnt lgkmcnt(12)
	ds_read_b64_tr_b16 v[198:199], v231 offset:45120
	ds_read_b64_tr_b16 v[200:201], v231 offset:47680
	v_exp_f32_e32 v100, v100
	v_exp_f32_e32 v101, v101
	v_add_f32_e32 v191, v191, v100
	v_add_f32_e32 v235, v235, v101
	v_cvt_pk_bf16_f32 v99, v100, v101
	v_mfma_f32_32x32x16_bf16 v[34:49], v[202:205], v[82:85], v[34:49]
	s_waitcnt lgkmcnt(12)
	ds_read_b64_tr_b16 v[202:203], v231 offset:45184
	ds_read_b64_tr_b16 v[204:205], v231 offset:47744
	v_exp_f32_e32 v102, v102
	v_exp_f32_e32 v103, v103
	s_cmp_lt_u32 s90, 2
	s_cbranch_scc0 .Ldf_dma_skip
	s_add_i32 m0, s100, 0x12000
	s_nop 0
	global_load_lds_dwordx4 v247, s[98:99]
.Ldf_dma_skip:
	v_add_f32_e32 v191, v191, v102
	v_add_f32_e32 v235, v235, v103
	v_cvt_pk_bf16_f32 v100, v102, v103
	v_mfma_f32_32x32x16_bf16 v[18:33], v[206:209], v[82:85], v[18:33]
	s_waitcnt lgkmcnt(12)
	ds_read_b64_tr_b16 v[206:207], v231 offset:45248
	ds_read_b64_tr_b16 v[208:209], v231 offset:47808
	v_exp_f32_e32 v104, v104
	v_exp_f32_e32 v105, v105
	v_add_f32_e32 v191, v191, v104
	v_add_f32_e32 v235, v235, v105
	v_cvt_pk_bf16_f32 v101, v104, v105
	v_mfma_f32_32x32x16_bf16 v[50:65], v[210:213], v[86:89], v[50:65]
	s_waitcnt lgkmcnt(12)
	ds_read_b64_tr_b16 v[210:211], v231 offset:50176
	ds_read_b64_tr_b16 v[212:213], v231 offset:52736
	v_exp_f32_e32 v106, v106
	v_exp_f32_e32 v107, v107
	v_add_f32_e32 v191, v191, v106
	v_add_f32_e32 v235, v235, v107
	v_cvt_pk_bf16_f32 v102, v106, v107
	v_mfma_f32_32x32x16_bf16 v[66:81], v[214:217], v[86:89], v[66:81]
	s_waitcnt lgkmcnt(12)
	ds_read_b64_tr_b16 v[214:215], v231 offset:50240
	ds_read_b64_tr_b16 v[216:217], v231 offset:52800
	v_exp_f32_e32 v108, v108
	v_exp_f32_e32 v109, v109
	v_add_f32_e32 v191, v191, v108
	v_add_f32_e32 v235, v235, v109
	v_cvt_pk_bf16_f32 v103, v108, v109
	v_mfma_f32_32x32x16_bf16 v[34:49], v[218:221], v[86:89], v[34:49]
	s_waitcnt lgkmcnt(12)
	ds_read_b64_tr_b16 v[218:219], v231 offset:50304
	ds_read_b64_tr_b16 v[220:221], v231 offset:52864
	v_exp_f32_e32 v110, v110
	v_exp_f32_e32 v111, v111
	v_add_f32_e32 v191, v191, v110
	v_add_f32_e32 v235, v235, v111
	v_cvt_pk_bf16_f32 v104, v110, v111
	v_mfma_f32_32x32x16_bf16 v[18:33], v[226:229], v[86:89], v[18:33]
	s_waitcnt lgkmcnt(12)
	ds_read_b64_tr_b16 v[226:227], v231 offset:50368
	ds_read_b64_tr_b16 v[228:229], v231 offset:52928
	v_exp_f32_e32 v112, v112
	v_exp_f32_e32 v113, v113
	v_add_f32_e32 v191, v191, v112
	v_add_f32_e32 v235, v235, v113
	v_cvt_pk_bf16_f32 v105, v112, v113
	v_mfma_f32_32x32x16_bf16 v[50:65], v[194:197], v[98:101], v[50:65]
	s_waitcnt lgkmcnt(12)
	ds_read_b64_tr_b16 v[194:195], v232 offset:20480
	ds_read_b64_tr_b16 v[196:197], v232 offset:23040
	v_exp_f32_e32 v114, v114
	v_exp_f32_e32 v115, v115
	v_add_f32_e32 v191, v191, v114
	v_add_f32_e32 v235, v235, v115
	v_cvt_pk_bf16_f32 v114, v114, v115
	v_mfma_f32_32x32x16_bf16 v[66:81], v[198:201], v[98:101], v[66:81]
	s_waitcnt lgkmcnt(12)
	ds_read_b64_tr_b16 v[198:199], v232 offset:20544
	ds_read_b64_tr_b16 v[200:201], v232 offset:23104
	v_exp_f32_e32 v116, v116
	v_exp_f32_e32 v117, v117
	v_add_f32_e32 v191, v191, v116
	v_add_f32_e32 v235, v235, v117
	v_cvt_pk_bf16_f32 v115, v116, v117
	v_mfma_f32_32x32x16_bf16 v[34:49], v[202:205], v[98:101], v[34:49]
	s_waitcnt lgkmcnt(12)
	ds_read_b64_tr_b16 v[202:203], v232 offset:20608
	ds_read_b64_tr_b16 v[204:205], v232 offset:23168
	v_exp_f32_e32 v118, v118
	v_exp_f32_e32 v119, v119
	v_add_f32_e32 v191, v191, v118
	v_add_f32_e32 v235, v235, v119
	v_cvt_pk_bf16_f32 v116, v118, v119
	v_mfma_f32_32x32x16_bf16 v[18:33], v[206:209], v[98:101], v[18:33]
	s_waitcnt lgkmcnt(12)
	ds_read_b64_tr_b16 v[206:207], v232 offset:20672
	ds_read_b64_tr_b16 v[208:209], v232 offset:23232
	v_exp_f32_e32 v120, v120
	v_exp_f32_e32 v121, v121
	v_add_f32_e32 v191, v191, v120
	v_add_f32_e32 v235, v235, v121
	v_cvt_pk_bf16_f32 v117, v120, v121
	v_mfma_f32_32x32x16_bf16 v[50:65], v[210:213], v[102:105], v[50:65]
	s_waitcnt lgkmcnt(12)
	ds_read_b64_tr_b16 v[210:211], v232 offset:25600
	ds_read_b64_tr_b16 v[212:213], v232 offset:28160
	v_exp_f32_e32 v122, v122
	v_exp_f32_e32 v123, v123
	v_add_f32_e32 v191, v191, v122
	v_add_f32_e32 v235, v235, v123
	v_cvt_pk_bf16_f32 v118, v122, v123
	v_mfma_f32_32x32x16_bf16 v[66:81], v[214:217], v[102:105], v[66:81]
	s_waitcnt lgkmcnt(12)
	ds_read_b64_tr_b16 v[214:215], v232 offset:25664
	ds_read_b64_tr_b16 v[216:217], v232 offset:28224
	v_exp_f32_e32 v124, v124
	v_exp_f32_e32 v125, v125
	v_add_f32_e32 v191, v191, v124
	v_add_f32_e32 v235, v235, v125
	v_cvt_pk_bf16_f32 v119, v124, v125
	v_mfma_f32_32x32x16_bf16 v[34:49], v[218:221], v[102:105], v[34:49]
	s_waitcnt lgkmcnt(12)
	ds_read_b64_tr_b16 v[218:219], v232 offset:25728
	ds_read_b64_tr_b16 v[220:221], v232 offset:28288
	v_exp_f32_e32 v126, v126
	v_exp_f32_e32 v127, v127
	v_add_f32_e32 v191, v191, v126
	v_add_f32_e32 v235, v235, v127
	v_cvt_pk_bf16_f32 v120, v126, v127
	v_mfma_f32_32x32x16_bf16 v[18:33], v[226:229], v[102:105], v[18:33]
	s_waitcnt lgkmcnt(12)
	ds_read_b64_tr_b16 v[226:227], v232 offset:25792
	ds_read_b64_tr_b16 v[228:229], v232 offset:28352
	v_exp_f32_e32 v128, v128
	v_exp_f32_e32 v129, v129
	v_add_f32_e32 v191, v191, v128
	v_add_f32_e32 v235, v235, v129
	v_cvt_pk_bf16_f32 v121, v128, v129
	v_mfma_f32_32x32x16_bf16 v[50:65], v[194:197], v[114:117], v[50:65]
	s_waitcnt lgkmcnt(12)
	ds_read_b64_tr_b16 v[194:195], v232 offset:30720
	ds_read_b64_tr_b16 v[196:197], v232 offset:33280
	v_exp_f32_e32 v130, v130
	v_exp_f32_e32 v131, v131
	v_add_f32_e32 v191, v191, v130
	v_add_f32_e32 v235, v235, v131
	v_cvt_pk_bf16_f32 v130, v130, v131
	v_mfma_f32_32x32x16_bf16 v[66:81], v[198:201], v[114:117], v[66:81]
	s_waitcnt lgkmcnt(12)
	ds_read_b64_tr_b16 v[198:199], v232 offset:30784
	ds_read_b64_tr_b16 v[200:201], v232 offset:33344
	v_exp_f32_e32 v132, v132
	v_exp_f32_e32 v133, v133
	v_add_f32_e32 v191, v191, v132
	v_add_f32_e32 v235, v235, v133
	v_cvt_pk_bf16_f32 v131, v132, v133
	v_mfma_f32_32x32x16_bf16 v[34:49], v[202:205], v[114:117], v[34:49]
	s_waitcnt lgkmcnt(12)
	ds_read_b64_tr_b16 v[202:203], v232 offset:30848
	ds_read_b64_tr_b16 v[204:205], v232 offset:33408
	v_exp_f32_e32 v134, v134
	v_exp_f32_e32 v135, v135
	v_add_f32_e32 v191, v191, v134
	v_add_f32_e32 v235, v235, v135
	v_cvt_pk_bf16_f32 v132, v134, v135
	v_mfma_f32_32x32x16_bf16 v[18:33], v[206:209], v[114:117], v[18:33]
	s_waitcnt lgkmcnt(12)
	ds_read_b64_tr_b16 v[206:207], v232 offset:30912
	ds_read_b64_tr_b16 v[208:209], v232 offset:33472
	v_exp_f32_e32 v136, v136
	v_exp_f32_e32 v137, v137
	v_add_f32_e32 v191, v191, v136
	v_add_f32_e32 v235, v235, v137
	v_cvt_pk_bf16_f32 v133, v136, v137
	v_mfma_f32_32x32x16_bf16 v[50:65], v[210:213], v[118:121], v[50:65]
	s_waitcnt lgkmcnt(12)
	ds_read_b64_tr_b16 v[210:211], v232 offset:35840
	ds_read_b64_tr_b16 v[212:213], v232 offset:38400
	v_exp_f32_e32 v138, v138
	v_exp_f32_e32 v139, v139
	v_add_f32_e32 v191, v191, v138
	v_add_f32_e32 v235, v235, v139
	v_cvt_pk_bf16_f32 v134, v138, v139
	v_mfma_f32_32x32x16_bf16 v[66:81], v[214:217], v[118:121], v[66:81]
	s_waitcnt lgkmcnt(12)
	ds_read_b64_tr_b16 v[214:215], v232 offset:35904
	ds_read_b64_tr_b16 v[216:217], v232 offset:38464
	v_exp_f32_e32 v140, v140
	v_exp_f32_e32 v141, v141
	v_add_f32_e32 v191, v191, v140
	v_add_f32_e32 v235, v235, v141
	v_cvt_pk_bf16_f32 v135, v140, v141
	v_mfma_f32_32x32x16_bf16 v[34:49], v[218:221], v[118:121], v[34:49]
	s_waitcnt lgkmcnt(12)
	ds_read_b64_tr_b16 v[218:219], v232 offset:35968
	ds_read_b64_tr_b16 v[220:221], v232 offset:38528
	v_exp_f32_e32 v142, v142
	v_exp_f32_e32 v143, v143
	v_add_f32_e32 v191, v191, v142
	v_add_f32_e32 v235, v235, v143
	v_cvt_pk_bf16_f32 v136, v142, v143
	v_mfma_f32_32x32x16_bf16 v[18:33], v[226:229], v[118:121], v[18:33]
	s_waitcnt lgkmcnt(12)
	ds_read_b64_tr_b16 v[226:227], v232 offset:36032
	ds_read_b64_tr_b16 v[228:229], v232 offset:38592
	v_exp_f32_e32 v144, v144
	v_exp_f32_e32 v145, v145
	v_add_f32_e32 v191, v191, v144
	v_add_f32_e32 v235, v235, v145
	v_cvt_pk_bf16_f32 v137, v144, v145
	v_mfma_f32_32x32x16_bf16 v[50:65], v[194:197], v[130:133], v[50:65]
	s_waitcnt lgkmcnt(12)
	v_mfma_f32_32x32x16_bf16 v[66:81], v[198:201], v[130:133], v[66:81]
	s_waitcnt lgkmcnt(10)
	v_mfma_f32_32x32x16_bf16 v[34:49], v[202:205], v[130:133], v[34:49]
	s_waitcnt lgkmcnt(8)
	v_mfma_f32_32x32x16_bf16 v[18:33], v[206:209], v[130:133], v[18:33]
	s_waitcnt vmcnt(0)
	s_add_i32 s72, s72, 1
	s_add_u32 s44, s44, 0x180000
	s_addc_u32 s45, s45, 0
	s_cmp_eq_u32 s44, 0x2e80000
	s_waitcnt lgkmcnt(0)
	s_barrier
	s_cbranch_scc0 .Ldf_loop
	v_mfma_f32_32x32x16_bf16 v[50:65], v[210:213], v[134:137], v[50:65]
	v_mfma_f32_32x32x16_bf16 v[66:81], v[214:217], v[134:137], v[66:81]
	v_mfma_f32_32x32x16_bf16 v[34:49], v[218:221], v[134:137], v[34:49]
	v_mfma_f32_32x32x16_bf16 v[18:33], v[226:229], v[134:137], v[18:33]
	v_add_u32_e32 v238, 0x21480, v185
	v_add_u32_e32 v239, 0x21e80, v185
	v_add_u32_e32 v240, 0x214c0, v185
	v_add_u32_e32 v241, 0x21ec0, v185
	v_add_u32_e32 v242, 0x22800, v185
	v_add_u32_e32 v243, 0x23200, v185
	v_add_u32_e32 v244, 0x22840, v185
	v_add_u32_e32 v245, 0x23240, v185
	v_add_u32_e32 v246, 0x22880, v185
	v_add_u32_e32 v247, 0x23280, v185
	v_add_u32_e32 v248, 0x228c0, v185
	v_add_u32_e32 v249, 0x232c0, v185
	v_add_u32_e32 v250, 0x23c00, v185
	v_add_u32_e32 v251, 0x24600, v185
	v_add_u32_e32 v252, 0x23c40, v185
	v_add_u32_e32 v253, 0x24640, v185
	v_add_f32_e32 v191, v191, v235
	v_add_u32_e32 v82, 0x12800, v181
	ds_read_b128 v[82:85], v82
	v_add_u32_e32 v90, 0x12820, v181
	v_add_u32_e32 v94, 0x12840, v181
	v_add_u32_e32 v86, 0x14a00, v181
	ds_read_b128 v[86:89], v86
	v_add_u32_e32 v98, 0x12860, v181
	s_waitcnt lgkmcnt(1)
	v_mfma_f32_32x32x16_bf16 v[114:129], v[82:85], v[158:161], v[2:17]
	ds_read_b128 v[82:85], v90
	v_add_u32_e32 v90, 0x14a20, v181
	ds_read_b128 v[90:93], v90
	s_waitcnt lgkmcnt(1)
	v_mfma_f32_32x32x16_bf16 v[114:129], v[82:85], v[154:157], v[114:129]
	ds_read_b128 v[82:85], v94
	v_add_u32_e32 v94, 0x14a40, v181
	ds_read_b128 v[94:97], v94
	s_waitcnt lgkmcnt(1)
	v_mfma_f32_32x32x16_bf16 v[114:129], v[82:85], v[150:153], v[114:129]
	ds_read_b128 v[82:85], v98
	v_add_u32_e32 v98, 0x14a60, v181
	ds_read_b128 v[130:133], v98
	v_mfma_f32_32x32x16_bf16 v[98:113], v[86:89], v[158:161], v[2:17]
	v_add_u32_e32 v86, 0x18e00, v181
	ds_read_b128 v[168:171], v86
	v_mfma_f32_32x32x16_bf16 v[98:113], v[90:93], v[154:157], v[98:113]
	s_waitcnt lgkmcnt(3)
	v_mfma_f32_32x32x16_bf16 v[98:113], v[94:97], v[150:153], v[98:113]
	s_waitcnt lgkmcnt(2)
	v_mfma_f32_32x32x16_bf16 v[114:129], v[82:85], v[146:149], v[114:129]
	v_add_u32_e32 v82, 0x16c00, v181
	ds_read_b128 v[82:85], v82
	s_waitcnt lgkmcnt(2)
	v_mfma_f32_32x32x16_bf16 v[98:113], v[130:133], v[146:149], v[98:113]
	s_nop 7
	v_exp_f32_e32 v163, v114
	v_exp_f32_e32 v165, v116
	v_exp_f32_e32 v162, v117
	v_exp_f32_e32 v116, v119
	v_exp_f32_e32 v117, v120
	v_exp_f32_e32 v114, v122
	v_exp_f32_e32 v122, v124
	s_waitcnt lgkmcnt(0)
	v_mfma_f32_32x32x16_bf16 v[130:145], v[82:85], v[158:161], v[2:17]
	v_add_u32_e32 v82, 0x16c20, v181
	ds_read_b128 v[172:175], v82
	v_exp_f32_e32 v166, v98
	v_exp_f32_e32 v98, v121
	v_exp_f32_e32 v119, v126
	v_exp_f32_e32 v120, v127
	v_exp_f32_e32 v121, v128
	v_mfma_f32_32x32x16_bf16 v[82:97], v[168:171], v[158:161], v[2:17]
	v_exp_f32_e32 v168, v99
	v_add_u32_e32 v99, 0x18e20, v181
	ds_read_b128 v[192:195], v99
	v_add_u32_e32 v99, 0x16c40, v181
	v_exp_f32_e32 v124, v129
	ds_read_b128 v[126:129], v99
	v_add_u32_e32 v99, 0x18e40, v181
	s_waitcnt lgkmcnt(2)
	v_mfma_f32_32x32x16_bf16 v[130:145], v[172:175], v[154:157], v[130:145]
	ds_read_b128 v[174:177], v99
	v_add_u32_e32 v99, 0x16c60, v181
	v_exp_f32_e32 v169, v100
	v_exp_f32_e32 v173, v101
	v_exp_f32_e32 v160, v102
	v_exp_f32_e32 v159, v103
	ds_read_b128 v[100:103], v99
	s_waitcnt lgkmcnt(3)
	v_mfma_f32_32x32x16_bf16 v[82:97], v[192:195], v[154:157], v[82:97]
	v_add_u32_e32 v99, 0x18e60, v181
	ds_read_b128 v[196:199], v99
	v_exp_f32_e32 v164, v115
	v_exp_f32_e32 v118, v118
	v_exp_f32_e32 v158, v108
	v_exp_f32_e32 v167, v109
	v_exp_f32_e32 v161, v110
	s_waitcnt lgkmcnt(3)
	v_mfma_f32_32x32x16_bf16 v[130:145], v[126:129], v[150:153], v[130:145]
	v_exp_f32_e32 v126, v113
	v_exp_f32_e32 v129, v107
	v_exp_f32_e32 v115, v123
	v_exp_f32_e32 v123, v125
	v_exp_f32_e32 v170, v104
	v_exp_f32_e32 v171, v105
	v_exp_f32_e32 v172, v106
	s_waitcnt lgkmcnt(2)
	v_mfma_f32_32x32x16_bf16 v[82:97], v[174:177], v[150:153], v[82:97]
	v_exp_f32_e32 v127, v111
	v_exp_f32_e32 v128, v112
	s_waitcnt lgkmcnt(1)
	v_mfma_f32_32x32x16_bf16 v[130:145], v[100:103], v[146:149], v[130:145]
	s_waitcnt lgkmcnt(0)
	v_mfma_f32_32x32x16_bf16 v[82:97], v[196:199], v[146:149], v[82:97]
	s_nop 9
	v_exp_f32_e32 v99, v130
	v_exp_f32_e32 v100, v131
	v_exp_f32_e32 v113, v132
	v_exp_f32_e32 v101, v133
	v_exp_f32_e32 v102, v134
	v_exp_f32_e32 v103, v135
	v_add_u32_e32 v131, 0x1ba00, v185
	v_exp_f32_e32 v130, v82
	v_add_u32_e32 v82, 0x1b000, v185
	ds_read_b64_tr_b16 v[132:133], v82
	ds_read_b64_tr_b16 v[134:135], v131
	v_add_u32_e32 v82, 0x1b040, v185
	v_exp_f32_e32 v107, v140
	v_exp_f32_e32 v108, v141
	v_exp_f32_e32 v109, v142
	v_exp_f32_e32 v110, v143
	v_add_u32_e32 v131, 0x1ba40, v185
	ds_read_b64_tr_b16 v[140:141], v82
	ds_read_b64_tr_b16 v[142:143], v131
	v_exp_f32_e32 v156, v84
	v_add_u32_e32 v82, 0x1b080, v185
	v_add_u32_e32 v84, 0x1ba80, v185
	v_exp_f32_e32 v131, v83
	v_exp_f32_e32 v157, v85
	ds_read_b64_tr_b16 v[82:83], v82
	ds_read_b64_tr_b16 v[84:85], v84
	v_exp_f32_e32 v104, v136
	v_exp_f32_e32 v105, v137
	v_exp_f32_e32 v106, v138
	v_exp_f32_e32 v125, v139
	v_cvt_pk_bf16_f32 v136, v163, v164
	v_cvt_pk_bf16_f32 v137, v165, v162
	v_cvt_pk_bf16_f32 v138, v118, v116
	v_cvt_pk_bf16_f32 v139, v117, v98
	v_exp_f32_e32 v174, v86
	v_add_u32_e32 v86, 0x1b0c0, v185
	s_waitcnt lgkmcnt(4)
	v_mfma_f32_32x32x16_bf16 v[50:65], v[132:135], v[136:139], v[50:65]
	v_exp_f32_e32 v175, v87
	v_add_u32_e32 v87, 0x1bac0, v185
	ds_read_b64_tr_b16 v[132:133], v86
	ds_read_b64_tr_b16 v[134:135], v87
	v_exp_f32_e32 v176, v88
	v_exp_f32_e32 v177, v89
	v_cvt_pk_bf16_f32 v86, v114, v115
	v_cvt_pk_bf16_f32 v87, v122, v123
	s_waitcnt lgkmcnt(2)
	v_mfma_f32_32x32x16_bf16 v[34:49], v[82:85], v[136:139], v[34:49]
	v_add_u32_e32 v82, 0x1c400, v185
	v_add_u32_e32 v84, 0x1ce00, v185
	ds_read_b64_tr_b16 v[82:83], v82
	ds_read_b64_tr_b16 v[84:85], v84
	v_cvt_pk_bf16_f32 v88, v119, v120
	v_cvt_pk_bf16_f32 v89, v121, v124
	v_exp_f32_e32 v192, v90
	v_add_u32_e32 v90, 0x1c440, v185
	v_mfma_f32_32x32x16_bf16 v[66:81], v[140:143], v[136:139], v[66:81]
	v_exp_f32_e32 v193, v91
	v_exp_f32_e32 v91, v93
	v_exp_f32_e32 v93, v95
	v_add_u32_e32 v95, 0x1c4c0, v185
	v_exp_f32_e32 v111, v144
	v_add_u32_e32 v144, 0x1ec40, v185
	v_exp_f32_e32 v112, v145
	s_waitcnt lgkmcnt(2)
	v_mfma_f32_32x32x16_bf16 v[18:33], v[132:135], v[136:139], v[18:33]
	v_add_u32_e32 v134, 0x1ce40, v185
	ds_read_b64_tr_b16 v[132:133], v90
	ds_read_b64_tr_b16 v[134:135], v134
	v_exp_f32_e32 v90, v92
	v_exp_f32_e32 v92, v94
	v_exp_f32_e32 v94, v96
	v_add_u32_e32 v96, 0x1cec0, v185
	v_cvt_pk_bf16_f32 v136, v166, v168
	s_waitcnt lgkmcnt(2)
	v_mfma_f32_32x32x16_bf16 v[50:65], v[82:85], v[86:89], v[50:65]
	v_add_u32_e32 v82, 0x1c480, v185
	v_add_u32_e32 v84, 0x1ce80, v185
	ds_read_b64_tr_b16 v[82:83], v82
	ds_read_b64_tr_b16 v[84:85], v84
	v_cvt_pk_bf16_f32 v137, v169, v173
	v_cvt_pk_bf16_f32 v138, v160, v159
	v_cvt_pk_bf16_f32 v139, v170, v171
	s_waitcnt lgkmcnt(0)
	v_mfma_f32_32x32x16_bf16 v[34:49], v[82:85], v[86:89], v[34:49]
	v_add_u32_e32 v82, 0x1d800, v185
	v_add_u32_e32 v84, 0x1e200, v185
	v_mfma_f32_32x32x16_bf16 v[66:81], v[132:135], v[86:89], v[66:81]
	ds_read_b64_tr_b16 v[132:133], v95
	ds_read_b64_tr_b16 v[134:135], v96
	ds_read_b64_tr_b16 v[82:83], v82
	ds_read_b64_tr_b16 v[84:85], v84
	v_add_u32_e32 v96, 0x1d880, v185
	v_exp_f32_e32 v95, v97
	v_add_u32_e32 v97, 0x1d8c0, v185
	s_waitcnt lgkmcnt(2)
	v_mfma_f32_32x32x16_bf16 v[18:33], v[132:135], v[86:89], v[18:33]
	v_add_u32_e32 v86, 0x1d840, v185
	v_add_u32_e32 v88, 0x1e240, v185
	v_add_u32_e32 v134, 0x1e2c0, v185
	ds_read_b64_tr_b16 v[86:87], v86
	ds_read_b64_tr_b16 v[88:89], v88
	s_waitcnt lgkmcnt(2)
	v_mfma_f32_32x32x16_bf16 v[50:65], v[82:85], v[136:139], v[50:65]
	v_add_u32_e32 v84, 0x1e280, v185
	ds_read_b64_tr_b16 v[82:83], v96
	ds_read_b64_tr_b16 v[84:85], v84
	ds_read_b64_tr_b16 v[132:133], v97
	ds_read_b64_tr_b16 v[134:135], v134
	v_add_u32_e32 v96, 0x1ec00, v185
	v_add_u32_e32 v97, 0x1f600, v185
	ds_read_b64_tr_b16 v[140:141], v96
	ds_read_b64_tr_b16 v[142:143], v97
	ds_read_b64_tr_b16 v[144:145], v144
	v_add_f32_e32 v96, 0, v166
	v_add_f32_e32 v96, v168, v96
	v_add_f32_e32 v96, v169, v96
	v_add_f32_e32 v96, v173, v96
	s_waitcnt lgkmcnt(5)
	v_mfma_f32_32x32x16_bf16 v[34:49], v[82:85], v[136:139], v[34:49]
	v_add_u32_e32 v82, 0x1f640, v185
	v_add_f32_e32 v97, v160, v96
	ds_read_b64_tr_b16 v[146:147], v82
	v_add_u32_e32 v82, 0x1ec80, v185
	v_add_f32_e32 v97, v159, v97
	ds_read_b64_tr_b16 v[148:149], v82
	v_add_u32_e32 v82, 0x1f680, v185
	v_add_f32_e32 v97, v170, v97
	ds_read_b64_tr_b16 v[150:151], v82
	v_add_u32_e32 v82, 0x1ecc0, v185
	v_add_f32_e32 v97, v171, v97
	v_mfma_f32_32x32x16_bf16 v[66:81], v[86:89], v[136:139], v[66:81]
	v_cvt_pk_bf16_f32 v86, v172, v129
	v_cvt_pk_bf16_f32 v87, v158, v167
	v_cvt_pk_bf16_f32 v88, v161, v127
	v_cvt_pk_bf16_f32 v89, v128, v126
	ds_read_b64_tr_b16 v[152:153], v82
	v_add_u32_e32 v82, 0x1f6c0, v185
	v_add_f32_e32 v97, v172, v97
	ds_read_b64_tr_b16 v[154:155], v82
	s_waitcnt lgkmcnt(6)
	v_mfma_f32_32x32x16_bf16 v[50:65], v[140:143], v[86:89], v[50:65]
	v_add_u32_e32 v140, 0x20000, v185
	v_add_u32_e32 v142, 0x20a00, v185
	v_add_f32_e32 v97, v129, v97
	ds_read_b64_tr_b16 v[140:141], v140
	ds_read_b64_tr_b16 v[142:143], v142
	v_add_f32_e32 v97, v158, v97
	v_add_f32_e32 v97, v167, v97
	v_mfma_f32_32x32x16_bf16 v[18:33], v[132:135], v[136:139], v[18:33]
	v_add_f32_e32 v97, v161, v97
	v_add_f32_e32 v97, v127, v97
	v_add_f32_e32 v97, v128, v97
	v_add_f32_e32 v97, v126, v97
	v_cvt_pk_bf16_f32 v136, v130, v131
	v_add_u32_e32 v129, 0x200c0, v185
	v_add_f32_e32 v97, v130, v97
	v_add_f32_e32 v130, 0, v163
	s_waitcnt lgkmcnt(4)
	v_mfma_f32_32x32x16_bf16 v[34:49], v[148:151], v[86:89], v[34:49]
	ds_read_b64_tr_b16 v[148:149], v129
	v_add_u32_e32 v129, 0x20ac0, v185
	v_add_u32_e32 v126, 0x21400, v185
	v_add_u32_e32 v128, 0x21e00, v185
	v_add_f32_e32 v130, v164, v130
	v_cvt_pk_bf16_f32 v82, v99, v100
	v_cvt_pk_bf16_f32 v83, v113, v101
	v_cvt_pk_bf16_f32 v84, v102, v103
	v_cvt_pk_bf16_f32 v85, v104, v105
	v_mfma_f32_32x32x16_bf16 v[66:81], v[144:147], v[86:89], v[66:81]
	ds_read_b64_tr_b16 v[150:151], v129
	ds_read_b64_tr_b16 v[126:127], v126
	ds_read_b64_tr_b16 v[128:129], v128
	v_add_f32_e32 v130, v165, v130
	v_add_f32_e32 v130, v162, v130
	v_add_f32_e32 v118, v118, v130
	v_add_f32_e32 v116, v116, v118
	s_waitcnt lgkmcnt(6)
	v_mfma_f32_32x32x16_bf16 v[18:33], v[152:155], v[86:89], v[18:33]
	v_add_u32_e32 v86, 0x20080, v185
	v_add_u32_e32 v88, 0x20a80, v185
	ds_read_b64_tr_b16 v[86:87], v86
	ds_read_b64_tr_b16 v[88:89], v88
	v_add_u32_e32 v144, 0x20040, v185
	v_add_u32_e32 v146, 0x20a40, v185
	v_add_f32_e32 v116, v117, v116
	s_waitcnt lgkmcnt(6)
	v_mfma_f32_32x32x16_bf16 v[50:65], v[140:143], v[82:85], v[50:65]
	ds_read_b64_tr_b16 v[144:145], v144
	ds_read_b64_tr_b16 v[146:147], v146
	v_add_f32_e32 v98, v98, v116
	v_add_f32_e32 v98, v114, v98
	v_add_f32_e32 v98, v115, v98
	v_cvt_pk_bf16_f32 v132, v106, v125
	v_cvt_pk_bf16_f32 v133, v107, v108
	v_cvt_pk_bf16_f32 v134, v109, v110
	v_cvt_pk_bf16_f32 v135, v111, v112
	v_add_f32_e32 v98, v122, v98
	v_add_f32_e32 v98, v123, v98
	s_waitcnt lgkmcnt(4)
	v_mfma_f32_32x32x16_bf16 v[50:65], v[126:129], v[132:135], v[50:65]
	v_add_f32_e32 v98, v119, v98
	v_add_f32_e32 v98, v120, v98
	v_add_f32_e32 v97, v131, v97
	v_add_f32_e32 v98, v121, v98
	v_add_u32_e32 v140, 0x21440, v185
	v_add_u32_e32 v142, 0x21e40, v185
	v_add_f32_e32 v97, v156, v97
	s_waitcnt lgkmcnt(2)
	v_mfma_f32_32x32x16_bf16 v[34:49], v[86:89], v[82:85], v[34:49]
	v_add_f32_e32 v98, v124, v98
	v_cvt_pk_bf16_f32 v137, v156, v157
	ds_read_b64_tr_b16 v[140:141], v140
	ds_read_b64_tr_b16 v[142:143], v142
	v_add_f32_e32 v97, v157, v97
	v_add_f32_e32 v98, v99, v98
	v_add_f32_e32 v98, v100, v98
	s_waitcnt lgkmcnt(2)
	v_mfma_f32_32x32x16_bf16 v[66:81], v[144:147], v[82:85], v[66:81]
	ds_read_b64_tr_b16 v[144:145], v238
	ds_read_b64_tr_b16 v[146:147], v239
	ds_read_b64_tr_b16 v[152:153], v240
	ds_read_b64_tr_b16 v[154:155], v241
	ds_read_b64_tr_b16 v[86:87], v242
	ds_read_b64_tr_b16 v[88:89], v243
	ds_read_b64_tr_b16 v[156:157], v244
	ds_read_b64_tr_b16 v[158:159], v245
	v_cvt_pk_bf16_f32 v138, v174, v175
	v_cvt_pk_bf16_f32 v139, v176, v177
	v_add_f32_e32 v98, v113, v98
	v_add_f32_e32 v97, v174, v97
	v_add_f32_e32 v97, v175, v97
	s_waitcnt lgkmcnt(2)
	v_mfma_f32_32x32x16_bf16 v[50:65], v[86:89], v[136:139], v[50:65]
	v_add_f32_e32 v86, v101, v98
	v_add_f32_e32 v86, v102, v86
	v_add_f32_e32 v86, v103, v86
	v_add_f32_e32 v97, v176, v97
	v_add_f32_e32 v86, v104, v86
	v_add_f32_e32 v97, v177, v97
	v_add_f32_e32 v86, v105, v86
	v_mfma_f32_32x32x16_bf16 v[34:49], v[144:147], v[132:135], v[34:49]
	v_add_f32_e32 v97, v192, v97
	v_add_f32_e32 v86, v106, v86
	v_add_f32_e32 v97, v193, v97
	v_add_f32_e32 v86, v125, v86
	v_add_f32_e32 v97, v90, v97
	v_add_f32_e32 v86, v107, v86
	v_add_f32_e32 v97, v91, v97
	v_mfma_f32_32x32x16_bf16 v[18:33], v[148:151], v[82:85], v[18:33]
	ds_read_b64_tr_b16 v[82:83], v246
	ds_read_b64_tr_b16 v[84:85], v247
	ds_read_b64_tr_b16 v[148:149], v248
	ds_read_b64_tr_b16 v[150:151], v249
	v_add_f32_e32 v86, v108, v86
	v_add_f32_e32 v97, v92, v97
	v_add_f32_e32 v86, v109, v86
	ds_read_b64_tr_b16 v[126:127], v250
	ds_read_b64_tr_b16 v[128:129], v251
	ds_read_b64_tr_b16 v[164:165], v252
	ds_read_b64_tr_b16 v[166:167], v253
	v_add_f32_e32 v97, v93, v97
	v_add_f32_e32 v86, v110, v86
	s_waitcnt lgkmcnt(6)
	v_mfma_f32_32x32x16_bf16 v[34:49], v[82:85], v[136:139], v[34:49]
	v_mov_b32_e32 v83, v179
	v_add_f32_e32 v97, v94, v97
	v_add_f32_e32 v86, v111, v86
	v_add_f32_e32 v97, v95, v97
	v_add_f32_e32 v86, v112, v86
	v_add_f32_e32 v86, v86, v97
	v_add_f32_e32 v82, v191, v86
	v_mfma_f32_32x32x16_bf16 v[66:81], v[140:143], v[132:135], v[66:81]
	ds_read_b64_tr_b16 v[140:141], v254
	ds_read_b64_tr_b16 v[142:143], v187
	ds_read_b64_tr_b16 v[160:161], v222
	ds_read_b64_tr_b16 v[162:163], v223
	s_waitcnt lgkmcnt(0)
	s_barrier
	v_cvt_pk_bf16_f32 v96, v192, v193
	v_mbcnt_lo_u32_b32 v83, -1, v83
	v_mfma_f32_32x32x16_bf16 v[18:33], v[152:155], v[132:135], v[18:33]
	v_mbcnt_hi_u32_b32 v87, -1, v83
	v_lshlrev_b32_e32 v83, 2, v87
	v_xor_b32_e32 v85, 0x80, v83
	ds_bpermute_b32 v83, v85, v82
	v_cvt_pk_bf16_f32 v97, v90, v91
	v_cvt_pk_bf16_f32 v98, v92, v93
	v_cvt_pk_bf16_f32 v99, v94, v95
	v_mfma_f32_32x32x16_bf16 v[66:81], v[156:159], v[136:139], v[66:81]
	s_waitcnt lgkmcnt(0)
	v_add_f32_e32 v82, v82, v83
	v_div_scale_f32 v83, s[44:45], v82, v82, 1.0
	v_rcp_f32_e32 v84, v83
	s_nop 0
	v_fma_f32 v86, -v83, v84, 1.0
	v_mfma_f32_32x32x16_bf16 v[18:33], v[148:151], v[136:139], v[18:33]
	v_fmac_f32_e32 v84, v86, v84
	v_div_scale_f32 v86, vcc, 1.0, v82, 1.0
	v_mul_f32_e32 v88, v86, v84
	v_fma_f32 v89, -v83, v88, v86
	v_fmac_f32_e32 v88, v89, v84
	v_fma_f32 v83, -v83, v88, v86
	v_mfma_f32_32x32x16_bf16 v[50:65], v[126:129], v[96:99], v[50:65]
	v_div_fmas_f32 v83, v83, v84, v88
	v_and_b32_e32 v86, 31, v87
	v_ashrrev_i32_e32 v87, 5, v87
	v_div_fixup_f32 v83, v83, v82, 1.0
	v_lshlrev_b32_e32 v82, 9, v87
	v_lshlrev_b32_e32 v88, 2, v86
	v_mul_f32_e32 v84, v224, v83
	v_mfma_f32_32x32x16_bf16 v[66:81], v[164:167], v[96:99], v[66:81]
	s_and_b64 vcc, exec, s[6:7]
	v_add3_u32 v82, s28, v82, v88
	v_mfma_f32_32x32x16_bf16 v[34:49], v[140:143], v[96:99], v[34:49]
	v_mfma_f32_32x32x16_bf16 v[18:33], v[160:163], v[96:99], v[18:33]
	s_cbranch_vccnz .LBB0_658
	v_mul_f32_e32 v88, v50, v84
	v_mul_f32_e32 v89, v51, v84
	ds_write2_b32 v82, v88, v89 offset1:32
	v_mul_f32_e32 v88, v52, v84
	v_mul_f32_e32 v89, v53, v84
	ds_write2_b32 v82, v88, v89 offset0:64 offset1:96
	v_mul_f32_e32 v88, v54, v84
	v_mul_f32_e32 v89, v55, v84
	v_add_u32_e32 v90, 0x400, v82
	ds_write2_b32 v90, v88, v89 offset1:32
	v_mul_f32_e32 v88, v56, v84
	v_mul_f32_e32 v89, v57, v84
	ds_write2_b32 v90, v88, v89 offset0:64 offset1:96
	v_mul_f32_e32 v88, v58, v84
	v_mul_f32_e32 v89, v59, v84
	v_add_u32_e32 v90, 0x800, v82
	ds_write2_b32 v90, v88, v89 offset1:32
	v_mul_f32_e32 v88, v60, v84
	v_mul_f32_e32 v89, v61, v84
	ds_write2_b32 v90, v88, v89 offset0:64 offset1:96
	v_mul_f32_e32 v88, v62, v84
	v_mul_f32_e32 v89, v63, v84
	v_add_u32_e32 v90, 0xc00, v82
	ds_write2_b32 v90, v88, v89 offset1:32
	v_mul_f32_e32 v88, v64, v84
	v_mul_f32_e32 v89, v65, v84
	ds_write2_b32 v90, v88, v89 offset0:64 offset1:96
	v_mul_f32_e32 v88, v66, v84
	v_mul_f32_e32 v89, v67, v84
	v_add_u32_e32 v90, 0x1000, v82
	ds_write2_b32 v90, v88, v89 offset1:32
	v_mul_f32_e32 v88, v68, v84
	v_mul_f32_e32 v89, v69, v84
	ds_write2_b32 v90, v88, v89 offset0:64 offset1:96
	v_mul_f32_e32 v88, v70, v84
	v_mul_f32_e32 v89, v71, v84
	v_add_u32_e32 v90, 0x1400, v82
	ds_write2_b32 v90, v88, v89 offset1:32
	v_mul_f32_e32 v88, v72, v84
	v_mul_f32_e32 v89, v73, v84
	ds_write2_b32 v90, v88, v89 offset0:64 offset1:96
	v_mul_f32_e32 v88, v74, v84
	v_mul_f32_e32 v89, v75, v84
	v_add_u32_e32 v90, 0x1800, v82
	ds_write2_b32 v90, v88, v89 offset1:32
	v_mul_f32_e32 v88, v76, v84
	v_mul_f32_e32 v89, v77, v84
	ds_write2_b32 v90, v88, v89 offset0:64 offset1:96
	v_mul_f32_e32 v88, v78, v84
	v_mul_f32_e32 v89, v79, v84
	v_add_u32_e32 v90, 0x1c00, v82
	ds_write2_b32 v90, v88, v89 offset1:32
	v_mul_f32_e32 v88, v80, v84
	v_mul_f32_e32 v89, v81, v84
	ds_write2_b32 v90, v88, v89 offset0:64 offset1:96
	v_mul_f32_e32 v88, v34, v84
	v_mul_f32_e32 v89, v35, v84
	v_add_u32_e32 v90, 0x2000, v82
	ds_write2_b32 v90, v88, v89 offset1:32
	v_mul_f32_e32 v88, v36, v84
	v_mul_f32_e32 v89, v37, v84
	ds_write2_b32 v90, v88, v89 offset0:64 offset1:96
	v_mul_f32_e32 v88, v38, v84
	v_mul_f32_e32 v89, v39, v84
	v_add_u32_e32 v90, 0x2400, v82
	ds_write2_b32 v90, v88, v89 offset1:32
	v_mul_f32_e32 v88, v40, v84
	v_mul_f32_e32 v89, v41, v84
	ds_write2_b32 v90, v88, v89 offset0:64 offset1:96
	v_mul_f32_e32 v88, v42, v84
	v_mul_f32_e32 v89, v43, v84
	v_add_u32_e32 v90, 0x2800, v82
	ds_write2_b32 v90, v88, v89 offset1:32
	v_mul_f32_e32 v88, v44, v84
	v_mul_f32_e32 v89, v45, v84
	ds_write2_b32 v90, v88, v89 offset0:64 offset1:96
	v_mul_f32_e32 v88, v46, v84
	v_mul_f32_e32 v89, v47, v84
	v_add_u32_e32 v90, 0x2c00, v82
	ds_write2_b32 v90, v88, v89 offset1:32
	v_mul_f32_e32 v88, v48, v84
	v_mul_f32_e32 v89, v49, v84
	ds_write2_b32 v90, v88, v89 offset0:64 offset1:96
	v_mul_f32_e32 v88, v18, v84
	v_mul_f32_e32 v89, v19, v84
	v_add_u32_e32 v90, 0x3000, v82
	ds_write2_b32 v90, v88, v89 offset1:32
	v_mul_f32_e32 v88, v20, v84
	v_mul_f32_e32 v89, v21, v84
	ds_write2_b32 v90, v88, v89 offset0:64 offset1:96
	v_mul_f32_e32 v88, v22, v84
	v_mul_f32_e32 v89, v23, v84
	v_add_u32_e32 v90, 0x3400, v82
	ds_write2_b32 v90, v88, v89 offset1:32
	v_mul_f32_e32 v88, v24, v84
	v_mul_f32_e32 v89, v25, v84
	ds_write2_b32 v90, v88, v89 offset0:64 offset1:96
	v_mul_f32_e32 v88, v26, v84
	v_mul_f32_e32 v89, v27, v84
	v_add_u32_e32 v90, 0x3800, v82
	ds_write2_b32 v90, v88, v89 offset1:32
	v_mul_f32_e32 v88, v28, v84
	v_mul_f32_e32 v89, v29, v84
	ds_write2_b32 v90, v88, v89 offset0:64 offset1:96
	v_mul_f32_e32 v88, v30, v84
	v_mul_f32_e32 v89, v31, v84
	v_add_u32_e32 v90, 0x3c00, v82
	ds_write2_b32 v90, v88, v89 offset1:32
	v_mul_f32_e32 v88, v32, v84
	v_mul_f32_e32 v89, v33, v84
	ds_write2_b32 v90, v88, v89 offset0:64 offset1:96
